# post1 row loop: four loop-invariant norm-weight and inverse-frequency table loads cached in registers before the loop (two fewer dependent memory round trips per row)
# speedup vs baseline: 1.0142x; 1.0021x over previous
; __device__ __forceinline__ void phase_post1(const Params& p, int layer, const int wave_s) {
;   int t_ = TIDX; asm volatile("" : "+v"(t_)); const int lane = t_ & 63, wave = __builtin_amdgcn_readfirstlane(t_ >> 6), gw = blockIdx.x * 8 + wave, NGW = gridDim.x * 8; (void)wave;
;   bf16_t* P = (bf16_t*)(p.ws + WS_P); bf16_t* POOL = (bf16_t*)(p.ws + WS_POOL); bf16_t* KC = (bf16_t*)(p.ws + WS_KC);
;   const float* aqn = p.a_q_norm + layer * 64; const float* akn = p.a_k_norm + layer * 64;
;   const float* bqn = p.b_q_norm + layer * 128; const float* bkn = p.b_k_norm + layer * 128;
;   const float* cql = p.c_q_lat + layer * 384; const float* ckvl = p.c_kv_lat + layer * 256; const float* ckn = p.c_k_norm + layer * 192;
;   for (int r = gw; r < MP; r += NGW) {
;     if (r >= LROWS) {
;       *(u32x4*)(POOL + (size_t)r * 512 + lane * 8) = (u32x4){0u, 0u, 0u, 0u};
;       for (int i = lane; i < 768 / 8; i += 64) *(u32x4*)(KC + (size_t)r * 768 + i * 8) = (u32x4){0u, 0u, 0u, 0u};
;       continue; }
;     bf16_t* pr = P + (size_t)r * INP;
;     const float posf = (float)r;
;     const float rowp = (r < NMETA) ? -1.f : (float)((r - NMETA) >> 6), colp = (r < NMETA) ? (float)r : (float)((r - NMETA) & 63);
;     { float x[16]; u32x4* ptr = (u32x4*)(pr + C_AQ + lane * 16); const u32x4 w0 = ptr[0], w1 = ptr[1]; unpack8(w0, x); unpack8(w1, x + 8);
;       float ss = 0.f;
; #pragma unroll
;       for (int i = 0; i < 16; ++i) ss += x[i] * x[i];
;       ss += __shfl_xor(ss, 1); ss += __shfl_xor(ss, 2);
;       const float rs = rsqrtf(ss * (1.f / 64.f) + EPS) * ((lane >> 5) ? 1.f : QS_A);
;       const float* wn = ((lane >> 5) ? akn : aqn) + (lane & 3) * 16;
; #pragma unroll
;       for (int i = 0; i < 16; ++i) x[i] = x[i] * rs * wn[i];
;       if ((lane & 3) == 0) {
; #pragma unroll
;         for (int j = 0; j < 8; ++j) { float c, s; rope_cs(posf, p.inv_a[j], c, s); const float x1 = x[j], x2 = x[8 + j]; x[j] = x1 * c - x2 * s; x[8 + j] = x1 * s + x2 * c; }
;       }
;       ptr[0] = pack8(x); ptr[1] = pack8(x + 8); }
; #pragma unroll
;     for (int pass = 0; pass < 2; ++pass) {
;       const bool act = (pass == 0) || (lane < 32);
;       u32x4* ptr = (u32x4*)(pr + (pass == 0 ? C_BQ : C_BK) + lane * 8);
;       float x[8]; u32x4 w = {0u, 0u, 0u, 0u}; if (act) w = *ptr; unpack8(w, x);
;       float ss = 0.f;
; #pragma unroll
;       for (int i = 0; i < 8; ++i) ss += x[i] * x[i];
.LBB0_201:
	s_or_b64 exec, exec, s[0:1]
	s_waitcnt lgkmcnt(0)
	s_barrier
	v_mbcnt_lo_u32_b32 v0, -1, 0
	v_mbcnt_hi_u32_b32 v0, -1, v0
	s_mul_i32 s22, s70, 0xc0
	v_or_b32_e32 v0, s61, v0
	s_nop 0
	v_readfirstlane_b32 s0, v0
	s_ashr_i32 s0, s0, 6
	s_add_i32 s4, s0, s75
	s_cmpk_gt_i32 s4, 0x40ff
	s_cbranch_scc1 .LBB0_216
	s_mul_i32 s0, s70, 0x180
	s_mov_b32 s1, s5
	v_readlane_b32 s40, v254, 27
	s_lshl_b64 s[0:1], s[0:1], 2
	v_readlane_b32 s52, v254, 39
	v_readlane_b32 s53, v254, 40
	s_add_u32 s0, s52, s0
	s_mov_b32 s23, s5
	v_readlane_b32 s24, v254, 15
	s_addc_u32 s1, s53, s1
	s_lshl_b32 s2, s70, 7
	s_lshl_b64 s[6:7], s[22:23], 2
	v_readlane_b32 s26, v254, 17
	v_and_b32_e32 v64, 63, v0
	v_readlane_b32 s27, v254, 18
	s_add_u32 s6, s26, s6
	v_readlane_b32 s41, v254, 28
	v_readlane_b32 s43, v254, 30
	s_addc_u32 s7, s27, s7
	s_lshl_b32 s8, s70, 8
	s_mov_b32 s9, s5
	v_cmp_gt_u32_e64 s[36:37], 32, v64
	v_mov_b32_e32 v1, 0x3e38aa3b
	v_readlane_b32 s42, v254, 29
	v_readlane_b32 s54, v254, 41
	s_lshl_b64 s[8:9], s[8:9], 2
	v_cndmask_b32_e64 v65, 1.0, v1, s[36:37]
	v_mov_b32_e32 v1, s43
	v_mov_b32_e32 v2, s41
	v_readlane_b32 s55, v254, 42
	s_add_u32 s8, s54, s8
	v_cndmask_b32_e64 v3, v1, v2, s[36:37]
	v_mov_b32_e32 v1, s42
	v_mov_b32_e32 v2, s40
	s_addc_u32 s9, s55, s9
	s_lshl_b32 s18, s70, 6
	s_mov_b32 s19, s5
	v_cndmask_b32_e64 v2, v1, v2, s[36:37]
	v_and_b32_e32 v1, 3, v0
	v_lshl_add_u64 v[2:3], s[18:19], 2, v[2:3]
	v_lshlrev_b32_e32 v4, 6, v1
	v_mov_b32_e32 v5, v169
	v_lshl_add_u64 v[66:67], v[2:3], 0, v[4:5]
	v_and_b32_e32 v2, 4, v0
	v_lshlrev_b32_e32 v168, 4, v64
	v_cmp_eq_u32_e64 s[42:43], 0, v2
	v_lshlrev_b32_e32 v2, 2, v64
	v_mov_b32_e32 v3, v169
	s_mov_b32 s3, s5
	v_lshl_add_u64 v[70:71], s[8:9], 0, v[168:169]
	v_lshl_add_u64 v[72:73], s[6:7], 0, v[2:3]
	v_and_b32_e32 v2, 31, v0
	v_readlane_b32 s8, v251, 0
	v_readlane_b32 s6, v252, 16
	v_readlane_b32 s48, v254, 35
	v_lshlrev_b32_e32 v2, 2, v2
	v_readlane_b32 s9, v251, 1
	v_readlane_b32 s7, v252, 17
	s_lshl_b64 s[2:3], s[2:3], 2
	v_readlane_b32 s44, v254, 31
	v_readlane_b32 s45, v254, 32
	v_readlane_b32 s49, v254, 36
	v_lshl_add_u64 v[74:75], s[8:9], 0, v[2:3]
	v_and_b32_e32 v2, 32, v0
	v_lshl_add_u64 v[76:77], s[6:7], 0, v[168:169]
	s_add_u32 s6, s48, s2
	v_readlane_b32 s50, v254, 37
	v_cmp_eq_u32_e64 s[38:39], 0, v1
	v_and_b32_e32 v1, 15, v0
	v_cmp_eq_u32_e64 s[44:45], 0, v2
	v_bfe_u32 v2, v0, 4, 2
	s_addc_u32 s7, s49, s3
	v_lshlrev_b32_e32 v0, 5, v0
	v_readlane_b32 s51, v254, 38
	v_cmp_gt_u32_e64 s[40:41], 8, v1
	v_lshlrev_b32_e64 v102, v2, 1
	v_lshlrev_b32_e32 v2, 5, v1
	v_and_b32_e32 v0, 0x60, v0
	v_mov_b32_e32 v1, v169
	s_add_u32 s2, s50, s2
	v_lshl_add_u64 v[80:81], s[8:9], 0, v[0:1]
	s_addc_u32 s3, s51, s3
	v_or_b32_e32 v0, 64, v64
	v_lshl_add_u64 v[78:79], s[6:7], 0, v[2:3]
	v_lshl_add_u64 v[82:83], s[2:3], 0, v[2:3]
	v_or_b32_e32 v2, 0x80, v64
	v_lshlrev_b32_e32 v6, 3, v0
	v_mov_b32_e32 v7, v169
	v_lshlrev_b32_e32 v68, 3, v64
	v_mov_b32_e32 v69, v169
	v_lshl_add_u64 v[86:87], s[0:1], 0, v[6:7]
	v_lshlrev_b32_e32 v6, 3, v2
	v_lshl_add_u64 v[84:85], s[0:1], 0, v[68:69]
	v_lshl_add_u64 v[88:89], s[0:1], 0, v[6:7]
	v_readlane_b32 s0, v252, 14
	v_lshlrev_b32_e32 v4, 1, v64
	v_readlane_b32 s1, v252, 15
	v_lshl_add_u64 v[92:93], s[10:11], 0, v[168:169]
	v_or_b32_e32 v69, 0xffffffc0, v64
	v_lshl_add_u64 v[90:91], s[0:1], 0, v[4:5]
	v_lshl_add_u64 v[94:95], s[0:1], 0, v[168:169]
	v_lshlrev_b32_e32 v100, 1, v168
	v_lshlrev_b32_e32 v103, 2, v0
	v_lshlrev_b32_e32 v104, 2, v2
	s_movk_i32 s18, 0x2000
	v_readlane_b32 s46, v254, 33
	v_readlane_b32 s47, v254, 34
	v_readlane_b32 s25, v254, 16
	global_load_dwordx4 v[114:117], v[80:81], off offset:216
	global_load_dwordx4 v[118:121], v[80:81], off offset:200
	global_load_dwordx4 v[122:125], v[78:79], off offset:16
	global_load_dwordx4 v[126:129], v[78:79], off
	s_waitcnt vmcnt(0)
	s_branch .LBB0_204

; __device__ __forceinline__ float sum16(float v) { v += __shfl_xor(v, 1); v += __shfl_xor(v, 2); v += __shfl_xor(v, 4); v += __shfl_xor(v, 8); return v; }
; __device__ __forceinline__ void unpack8(const u32x4 w, float* x) { x[0] = bflo(w.x); x[1] = bfhi(w.x); x[2] = bflo(w.y); x[3] = bfhi(w.y); x[4] = bflo(w.z); x[5] = bfhi(w.z); x[6] = bflo(w.w); x[7] = bfhi(w.w); }
; __device__ __forceinline__ void phase_post1(const Params& p, int layer, const int wave_s) {
;     ...
;     const float rowp = (r < NMETA) ? -1.f : (float)((r - NMETA) >> 6), colp = (r < NMETA) ? (float)r : (float)((r - NMETA) & 63);
;     { float x[16]; u32x4* ptr = (u32x4*)(pr + C_AQ + lane * 16); const u32x4 w0 = ptr[0], w1 = ptr[1]; unpack8(w0, x); unpack8(w1, x + 8);
;       float ss = 0.f;
; #pragma unroll
;       for (int i = 0; i < 16; ++i) ss += x[i] * x[i];
;       ss += __shfl_xor(ss, 1); ss += __shfl_xor(ss, 2);
;       const float rs = rsqrtf(ss * (1.f / 64.f) + EPS) * ((lane >> 5) ? 1.f : QS_A);
;       const float* wn = ((lane >> 5) ? akn : aqn) + (lane & 3) * 16;
; #pragma unroll
;       for (int i = 0; i < 16; ++i) x[i] = x[i] * rs * wn[i];
;       if ((lane & 3) == 0) {
; #pragma unroll
;         for (int j = 0; j < 8; ++j) { float c, s; rope_cs(posf, p.inv_a[j], c, s); const float x1 = x[j], x2 = x[8 + j]; x[j] = x1 * c - x2 * s; x[8 + j] = x1 * s + x2 * c; }
;       }
;       ptr[0] = pack8(x); ptr[1] = pack8(x + 8); }
; #pragma unroll
;     for (int pass = 0; pass < 2; ++pass) {
;       const bool act = (pass == 0) || (lane < 32);
;       u32x4* ptr = (u32x4*)(pr + (pass == 0 ? C_BQ : C_BK) + lane * 8);
;       float x[8]; u32x4 w = {0u, 0u, 0u, 0u}; if (act) w = *ptr; unpack8(w, x);
;       float ss = 0.f;
; #pragma unroll
;       for (int i = 0; i < 8; ++i) ss += x[i] * x[i];
;       ss = sum16(ss);
;       const float rs = rsqrtf(ss * (1.f / 128.f) + EPS) * (pass == 0 ? QS_B : 1.f);
;       const int a = lane & 15; const float* wn = (pass == 0 ? bqn : bkn) + a * 8;
;       const float posv = (a < 8) ? rowp : colp;
; #pragma unroll
;       for (int i = 0; i < 8; ++i) { const float y = x[i] * rs * wn[i]; const float other = __shfl_xor(y, 4);
;         float c, s; rope_cs(posv, p.inv_b[(a & 3) * 8 + i], c, s);
;         x[i] = (a & 4) ? other * s + y * c : y * c - other * s; }
.LBB0_207:
	s_or_b64 exec, exec, s[0:1]
	s_add_i32 s0, s4, -16
	s_ashr_i32 s1, s0, 6
	s_and_b32 s0, s0, 63
	s_cmp_lt_i32 s4, 16
	v_cvt_f32_ubyte0_e32 v11, s0
	s_cselect_b64 vcc, -1, 0
	v_cndmask_b32_e32 v22, v11, v38, vcc
	v_bfe_u32 v11, v18, 16, 1
	v_add3_u32 v11, v18, v11, s15
	v_bfe_u32 v18, v19, 16, 1
	v_lshrrev_b32_e32 v11, 16, v11
	v_add3_u32 v18, v19, v18, s15
	v_and_or_b32 v18, v18, s14, v11
	v_bfe_u32 v11, v16, 16, 1
	v_add3_u32 v11, v16, v11, s15
	v_bfe_u32 v16, v17, 16, 1
	v_lshrrev_b32_e32 v11, 16, v11
	v_add3_u32 v16, v17, v16, s15
	v_and_or_b32 v19, v16, s14, v11
	v_bfe_u32 v11, v14, 16, 1
	v_add3_u32 v11, v14, v11, s15
	v_bfe_u32 v14, v15, 16, 1
	v_lshrrev_b32_e32 v11, 16, v11
	v_add3_u32 v14, v15, v14, s15
	v_and_or_b32 v20, v14, s14, v11
	v_bfe_u32 v11, v10, 16, 1
	v_add3_u32 v10, v10, v11, s15
	v_bfe_u32 v11, v12, 16, 1
	v_lshrrev_b32_e32 v10, 16, v10
	v_add3_u32 v11, v12, v11, s15
	v_and_or_b32 v21, v11, s14, v10
	v_bfe_u32 v10, v8, 16, 1
	v_add3_u32 v8, v8, v10, s15
	v_bfe_u32 v10, v9, 16, 1
	v_lshrrev_b32_e32 v8, 16, v8
	v_add3_u32 v9, v9, v10, s15
	v_and_or_b32 v8, v9, s14, v8
	v_bfe_u32 v9, v4, 16, 1
	v_add3_u32 v4, v4, v9, s15
	v_bfe_u32 v9, v5, 16, 1
	v_lshrrev_b32_e32 v4, 16, v4
	v_add3_u32 v5, v5, v9, s15
	v_and_or_b32 v9, v5, s14, v4
	v_bfe_u32 v4, v2, 16, 1
	v_add3_u32 v2, v2, v4, s15
	v_bfe_u32 v4, v3, 16, 1
	v_cvt_f32_i32_e32 v7, s1
	v_lshrrev_b32_e32 v2, 16, v2
	v_add3_u32 v3, v3, v4, s15
	v_and_or_b32 v10, v3, s14, v2
	v_bfe_u32 v2, v6, 16, 1
	v_add3_u32 v2, v6, v2, s15
	v_bfe_u32 v3, v13, 16, 1
	v_lshrrev_b32_e32 v2, 16, v2
	v_add3_u32 v3, v13, v3, s15
	v_cndmask_b32_e64 v7, v7, -1.0, vcc
	v_and_or_b32 v11, v3, s14, v2
	v_lshlrev_b32_e32 v168, 1, v68
	v_cmp_lt_i32_e32 vcc, v200, v197
	global_store_dwordx4 v[0:1], v[18:21], off
	global_store_dwordx4 v[0:1], v[8:11], off offset:16
	v_lshl_add_u64 v[12:13], s[34:35], 0, v[168:169]
	v_cndmask_b32_e32 v0, v196, v200, vcc
	v_cmp_lt_i32_e32 vcc, v201, v197
	s_movk_i32 s0, 0x1000
	v_lshlrev_b32_e32 v42, 2, v0
	v_cndmask_b32_e32 v0, v196, v201, vcc
	v_add_co_u32_e32 v14, vcc, s0, v12
	v_lshlrev_b32_e32 v41, 2, v0
	s_nop 0
	v_addc_co_u32_e32 v15, vcc, 0, v13, vcc
	v_cndmask_b32_e64 v43, v22, v7, s[40:41]
	global_load_dwordx4 v[0:3], v[14:15], off
	global_load_dwordx4 v[4:7], v[80:81], off offset:216
	global_load_dwordx4 v[8:11], v[80:81], off offset:200
	s_mov_b32 s0, 0x6dc9c883
	s_mov_b32 s1, 0x3fc45f30
	s_waitcnt vmcnt(2)
	v_lshlrev_b32_e32 v33, 16, v1
	s_waitcnt vmcnt(1)
	v_mul_f32_e32 v4, v43, v4
	s_waitcnt vmcnt(0)
	v_mul_f32_e32 v8, v43, v8
	v_cvt_f64_f32_e32 v[16:17], v8
	v_mul_f64 v[18:19], v[16:17], s[0:1]
	v_rndne_f64_e32 v[18:19], v[18:19]
	v_fma_f64 v[16:17], v[16:17], s[0:1], -v[18:19]
	v_cvt_f32_f64_e32 v8, v[16:17]
	v_cos_f32_e32 v16, v8
	v_sin_f32_e32 v18, v8
	v_mul_f32_e32 v8, v43, v9
	v_cvt_f64_f32_e32 v[8:9], v8
	v_mul_f64 v[20:21], v[8:9], s[0:1]
	v_rndne_f64_e32 v[20:21], v[20:21]
	v_fma_f64 v[8:9], v[8:9], s[0:1], -v[20:21]
	v_cvt_f32_f64_e32 v8, v[8:9]
	v_cos_f32_e32 v20, v8
	v_sin_f32_e32 v22, v8
	v_mul_f32_e32 v8, v43, v10
	v_cvt_f64_f32_e32 v[8:9], v8
	v_mul_f64 v[24:25], v[8:9], s[0:1]
	v_rndne_f64_e32 v[24:25], v[24:25]
	v_fma_f64 v[8:9], v[8:9], s[0:1], -v[24:25]
	v_cvt_f32_f64_e32 v8, v[8:9]
	v_cos_f32_e32 v17, v8
	v_sin_f32_e32 v19, v8
	v_mul_f32_e32 v8, v43, v11
	v_cvt_f64_f32_e32 v[8:9], v8
	v_mul_f64 v[10:11], v[8:9], s[0:1]
	v_rndne_f64_e32 v[10:11], v[10:11]
	v_fma_f64 v[8:9], v[8:9], s[0:1], -v[10:11]
	v_cvt_f32_f64_e32 v8, v[8:9]
	v_cos_f32_e32 v21, v8
	v_sin_f32_e32 v23, v8
	v_cvt_f64_f32_e32 v[8:9], v4
	v_mul_f64 v[10:11], v[8:9], s[0:1]
	v_rndne_f64_e32 v[10:11], v[10:11]
	v_fma_f64 v[8:9], v[8:9], s[0:1], -v[10:11]
	v_cvt_f32_f64_e32 v4, v[8:9]
	v_cos_f32_e32 v26, v4
	v_sin_f32_e32 v30, v4
	v_mul_f32_e32 v4, v43, v5
	v_cvt_f64_f32_e32 v[4:5], v4
	v_mul_f64 v[8:9], v[4:5], s[0:1]
	v_rndne_f64_e32 v[8:9], v[8:9]
	v_fma_f64 v[4:5], v[4:5], s[0:1], -v[8:9]
	v_cvt_f32_f64_e32 v4, v[4:5]
	v_cos_f32_e32 v24, v4
	v_sin_f32_e32 v28, v4
	v_mul_f32_e32 v4, v43, v6
	v_cvt_f64_f32_e32 v[4:5], v4
	v_mul_f64 v[8:9], v[4:5], s[0:1]
	v_rndne_f64_e32 v[8:9], v[8:9]
	v_fma_f64 v[4:5], v[4:5], s[0:1], -v[8:9]
	v_cvt_f32_f64_e32 v4, v[4:5]
	v_cos_f32_e32 v27, v4
	v_sin_f32_e32 v31, v4
	v_mul_f32_e32 v4, v43, v7
	v_cvt_f64_f32_e32 v[4:5], v4
	v_mul_f64 v[6:7], v[4:5], s[0:1]
	v_rndne_f64_e32 v[6:7], v[6:7]
	v_fma_f64 v[4:5], v[4:5], s[0:1], -v[6:7]
	v_cvt_f32_f64_e32 v4, v[4:5]
	v_and_b32_e32 v1, 0xffff0000, v1
	v_cos_f32_e32 v25, v4
	v_sin_f32_e32 v29, v4
	v_mov_b32_e32 v4, v1
	v_mov_b32_e32 v5, v33
	v_pk_mul_f32 v[34:35], v[4:5], v[4:5]
	v_mov_b32_e32 v4, v122
	v_mov_b32_e32 v5, v123
	v_mov_b32_e32 v6, v124
	v_mov_b32_e32 v7, v125
	v_mov_b32_e32 v8, v126
	v_mov_b32_e32 v9, v127
	v_mov_b32_e32 v10, v128
	v_mov_b32_e32 v11, v129
	v_lshlrev_b32_e32 v32, 16, v0
	v_and_b32_e32 v0, 0xffff0000, v0
	s_mov_b64 s[0:1], 0x1400

; __device__ __forceinline__ float sum16(float v) { v += __shfl_xor(v, 1); v += __shfl_xor(v, 2); v += __shfl_xor(v, 4); v += __shfl_xor(v, 8); return v; }
; __device__ __forceinline__ void phase_post1(const Params& p, int layer, const int wave_s) {
;     ...
;       float ss = 0.f;
; #pragma unroll
;       for (int i = 0; i < 8; ++i) ss += x[i] * x[i];
;       ss = sum16(ss);
;       const float rs = rsqrtf(ss * (1.f / 128.f) + EPS) * (pass == 0 ? QS_B : 1.f);
;       const int a = lane & 15; const float* wn = (pass == 0 ? bqn : bkn) + a * 8;
;       const float posv = (a < 8) ? rowp : colp;
; #pragma unroll
;       for (int i = 0; i < 8; ++i) { const float y = x[i] * rs * wn[i]; const float other = __shfl_xor(y, 4);
	v_mov_b32_e32 v48, v4
	v_mul_f32_e32 v4, v32, v32

; __device__ __forceinline__ float sum16(float v) { v += __shfl_xor(v, 1); v += __shfl_xor(v, 2); v += __shfl_xor(v, 4); v += __shfl_xor(v, 8); return v; }
; __device__ __forceinline__ void unpack8(const u32x4 w, float* x) { x[0] = bflo(w.x); x[1] = bfhi(w.x); x[2] = bflo(w.y); x[3] = bfhi(w.y); x[4] = bflo(w.z); x[5] = bfhi(w.z); x[6] = bflo(w.w); x[7] = bfhi(w.w); }
; __device__ __forceinline__ u32x4 pack8(const float* x) { u32x4 w; w.x = pk2(x[0], x[1]); w.y = pk2(x[2], x[3]); w.z = pk2(x[4], x[5]); w.w = pk2(x[6], x[7]); return w; }
; __device__ __forceinline__ void phase_post1(const Params& p, int layer, const int wave_s) {
;     ...
;     for (int pass = 0; pass < 2; ++pass) {
;       const bool act = (pass == 0) || (lane < 32);
;       u32x4* ptr = (u32x4*)(pr + (pass == 0 ? C_BQ : C_BK) + lane * 8);
;       float x[8]; u32x4 w = {0u, 0u, 0u, 0u}; if (act) w = *ptr; unpack8(w, x);
;       float ss = 0.f;
; #pragma unroll
;       for (int i = 0; i < 8; ++i) ss += x[i] * x[i];
;       ss = sum16(ss);
;       const float rs = rsqrtf(ss * (1.f / 128.f) + EPS) * (pass == 0 ? QS_B : 1.f);
;       const int a = lane & 15; const float* wn = (pass == 0 ? bqn : bkn) + a * 8;
;       const float posv = (a < 8) ? rowp : colp;
; #pragma unroll
;       for (int i = 0; i < 8; ++i) { const float y = x[i] * rs * wn[i]; const float other = __shfl_xor(y, 4);
;         float c, s; rope_cs(posv, p.inv_b[(a & 3) * 8 + i], c, s);
;         x[i] = (a & 4) ? other * s + y * c : y * c - other * s; }
;       if (act) *ptr = pack8(x);
	v_mov_b32_e32 v36, v8
	v_lshlrev_b32_e32 v8, 16, v2
	v_and_b32_e32 v2, 0xffff0000, v2
	v_fmac_f32_e32 v4, v0, v0
	v_mov_b32_e32 v44, v2
	v_mov_b32_e32 v45, v8
	v_add_f32_e32 v4, v35, v4
	v_mov_b32_e32 v37, v10
	v_mov_b32_e32 v10, v9
	v_lshlrev_b32_e32 v9, 16, v3
	v_and_b32_e32 v3, 0xffff0000, v3
	v_pk_mul_f32 v[44:45], v[44:45], v[44:45]
	v_add_f32_e32 v4, v34, v4
	v_mov_b32_e32 v46, v3
	v_mov_b32_e32 v47, v9
	v_add_f32_e32 v4, v45, v4
	v_pk_mul_f32 v[46:47], v[46:47], v[46:47]
	v_add_f32_e32 v4, v44, v4
	v_add_f32_e32 v4, v47, v4
	v_add_f32_e32 v4, v46, v4
	v_mov_b32_e32 v49, v6
	v_mov_b32_e32 v6, v5
	ds_bpermute_b32 v5, v39, v4
	s_waitcnt lgkmcnt(0)
	v_add_f32_e32 v4, v4, v5
	ds_bpermute_b32 v5, v40, v4
	s_waitcnt lgkmcnt(0)
	v_add_f32_e32 v4, v4, v5
	ds_bpermute_b32 v5, v42, v4
	s_waitcnt lgkmcnt(0)
	v_add_f32_e32 v4, v4, v5
	ds_bpermute_b32 v5, v41, v4
	s_waitcnt lgkmcnt(0)
	v_add_f32_e32 v4, v4, v5
	v_fmamk_f32 v4, v4, 0x3c000000, v170
	v_cmp_gt_f32_e32 vcc, s94, v4
	v_mul_f32_e32 v5, 0x4b800000, v4
	s_nop 0
	v_cndmask_b32_e32 v4, v4, v5, vcc
	v_rsq_f32_e32 v4, v4
	s_nop 0
	v_mul_f32_e32 v5, 0x45800000, v4
	v_cndmask_b32_e32 v4, v4, v5, vcc
	v_mul_f32_e32 v4, 0x3e0293ee, v4
	v_pk_mul_f32 v[0:1], v[4:5], v[0:1] op_sel_hi:[0,1]
	v_pk_mul_f32 v[0:1], v[10:11], v[0:1]
	v_pk_mul_f32 v[2:3], v[4:5], v[2:3] op_sel_hi:[0,1]
	v_pk_mul_f32 v[32:33], v[4:5], v[32:33] op_sel_hi:[0,1]
	ds_bpermute_b32 v10, v42, v0
	ds_bpermute_b32 v11, v42, v1
	v_pk_mul_f32 v[8:9], v[4:5], v[8:9] op_sel_hi:[0,1]
	v_pk_mul_f32 v[2:3], v[6:7], v[2:3]
	v_pk_mul_f32 v[32:33], v[36:37], v[32:33]
	v_pk_mul_f32 v[8:9], v[48:49], v[8:9]
	ds_bpermute_b32 v4, v42, v2
	ds_bpermute_b32 v5, v42, v3
	ds_bpermute_b32 v34, v42, v32
	ds_bpermute_b32 v35, v42, v33
	ds_bpermute_b32 v36, v42, v8
	ds_bpermute_b32 v37, v42, v9
	s_waitcnt lgkmcnt(6)
	v_pk_mul_f32 v[10:11], v[22:23], v[10:11]
	s_waitcnt lgkmcnt(4)
	v_pk_mul_f32 v[4:5], v[28:29], v[4:5]
	v_cndmask_b32_e64 v11, v11, -v11, s[42:43]
	v_cndmask_b32_e64 v10, v10, -v10, s[42:43]
	s_waitcnt lgkmcnt(2)
	v_pk_mul_f32 v[6:7], v[18:19], v[34:35]
	v_pk_fma_f32 v[0:1], v[0:1], v[20:21], v[10:11]
	s_waitcnt lgkmcnt(0)
	v_pk_mul_f32 v[10:11], v[30:31], v[36:37]
	v_cndmask_b32_e64 v5, v5, -v5, s[42:43]
	v_cndmask_b32_e64 v4, v4, -v4, s[42:43]
	v_cndmask_b32_e64 v7, v7, -v7, s[42:43]
	v_cndmask_b32_e64 v6, v6, -v6, s[42:43]
	v_cndmask_b32_e64 v11, v11, -v11, s[42:43]
	v_cndmask_b32_e64 v10, v10, -v10, s[42:43]
	v_pk_fma_f32 v[2:3], v[2:3], v[24:25], v[4:5]
	v_pk_fma_f32 v[6:7], v[32:33], v[16:17], v[6:7]
	v_pk_fma_f32 v[8:9], v[8:9], v[26:27], v[10:11]
	v_bfe_u32 v4, v3, 16, 1
	v_bfe_u32 v5, v2, 16, 1
	v_bfe_u32 v10, v1, 16, 1
	v_bfe_u32 v11, v0, 16, 1
	v_add3_u32 v0, v0, v11, s15
	v_add3_u32 v1, v1, v10, s15
	v_add3_u32 v2, v2, v5, s15
	v_add3_u32 v3, v3, v4, s15
	v_bfe_u32 v4, v6, 16, 1
	v_bfe_u32 v5, v7, 16, 1
	v_bfe_u32 v10, v8, 16, 1
	v_bfe_u32 v11, v9, 16, 1
	v_add3_u32 v9, v9, v11, s15
	v_add3_u32 v8, v8, v10, s15
	v_add3_u32 v5, v7, v5, s15
	v_add3_u32 v4, v6, v4, s15
	v_lshrrev_b32_e32 v4, 16, v4
	v_lshrrev_b32_e32 v5, 16, v5
	v_lshrrev_b32_e32 v6, 16, v8
	v_lshrrev_b32_e32 v7, 16, v9
	v_and_or_b32 v3, v3, s14, v7
	v_and_or_b32 v2, v2, s14, v6
	v_and_or_b32 v1, v1, s14, v5
	v_and_or_b32 v0, v0, s14, v4
	global_store_dwordx4 v[14:15], v[0:3], off
	v_lshl_add_u64 v[4:5], v[12:13], 0, s[0:1]
	s_nop 0
	v_mov_b32_e32 v0, 0
	v_mov_b32_e32 v1, 0
	v_mov_b32_e32 v2, 0
	v_mov_b32_e32 v3, 0
	s_and_saveexec_b64 s[0:1], s[36:37]
	s_cbranch_execz .LBB0_209
	global_load_dwordx4 v[0:3], v[4:5], off
.LBB0_209:
	s_or_b64 exec, exec, s[0:1]
	global_load_dwordx4 v[6:9], v[82:83], off
	global_load_dwordx4 v[10:13], v[82:83], off offset:16
	s_waitcnt vmcnt(2)
	v_lshlrev_b32_e32 v15, 16, v1
	v_lshlrev_b32_e32 v14, 16, v0
	v_and_b32_e32 v1, 0xffff0000, v1
	v_and_b32_e32 v0, 0xffff0000, v0
	v_mov_b32_e32 v18, v1
	v_mov_b32_e32 v19, v15
	v_mul_f32_e32 v24, v14, v14
	v_lshlrev_b32_e32 v16, 16, v2
	v_and_b32_e32 v2, 0xffff0000, v2
	v_pk_mul_f32 v[18:19], v[18:19], v[18:19]
	v_fmac_f32_e32 v24, v0, v0
	v_mov_b32_e32 v20, v2
	v_mov_b32_e32 v21, v16
	v_add_f32_e32 v19, v19, v24
	v_lshlrev_b32_e32 v17, 16, v3
	v_and_b32_e32 v3, 0xffff0000, v3
	v_pk_mul_f32 v[20:21], v[20:21], v[20:21]
	v_add_f32_e32 v18, v18, v19
	v_mov_b32_e32 v22, v3
	v_mov_b32_e32 v23, v17
	v_add_f32_e32 v18, v21, v18
	v_pk_mul_f32 v[22:23], v[22:23], v[22:23]
	v_add_f32_e32 v18, v20, v18
	v_add_f32_e32 v18, v23, v18
	v_add_f32_e32 v18, v22, v18
	ds_bpermute_b32 v19, v39, v18
	s_bfe_i64 s[28:29], s[4:5], 0x200000
	s_waitcnt lgkmcnt(0)
	v_add_f32_e32 v18, v18, v19
	ds_bpermute_b32 v19, v40, v18
	s_waitcnt lgkmcnt(0)
	v_add_f32_e32 v18, v18, v19
	ds_bpermute_b32 v19, v42, v18
	s_waitcnt lgkmcnt(0)
	v_add_f32_e32 v18, v18, v19
	ds_bpermute_b32 v19, v41, v18
	s_waitcnt lgkmcnt(0)
	v_add_f32_e32 v18, v18, v19
	v_fmamk_f32 v18, v18, 0x3c000000, v170
	v_mul_f32_e32 v19, 0x4b800000, v18
	v_cmp_gt_f32_e32 vcc, s94, v18
	s_nop 1
	v_cndmask_b32_e32 v18, v18, v19, vcc
	v_rsq_f32_e32 v18, v18
	s_nop 0
	v_mul_f32_e32 v19, 0x45800000, v18
	v_cndmask_b32_e32 v18, v18, v19, vcc
	v_pk_mul_f32 v[14:15], v[18:19], v[14:15] op_sel_hi:[0,1]
	v_pk_mul_f32 v[0:1], v[18:19], v[0:1] op_sel_hi:[0,1]
	v_pk_mul_f32 v[16:17], v[18:19], v[16:17] op_sel_hi:[0,1]
	v_pk_mul_f32 v[2:3], v[18:19], v[2:3] op_sel_hi:[0,1]
	s_waitcnt vmcnt(1)
	v_mov_b32_e32 v18, v6
	v_mov_b32_e32 v19, v8
	v_mov_b32_e32 v8, v7
	s_waitcnt vmcnt(0)
	v_mov_b32_e32 v6, v10
	v_mov_b32_e32 v7, v12
	v_mov_b32_e32 v12, v11
	v_pk_mul_f32 v[18:19], v[18:19], v[14:15]
	v_pk_mul_f32 v[14:15], v[8:9], v[0:1]
	v_pk_mul_f32 v[10:11], v[6:7], v[16:17]
	v_pk_mul_f32 v[6:7], v[12:13], v[2:3]
	ds_bpermute_b32 v20, v42, v18
	ds_bpermute_b32 v16, v42, v14
	ds_bpermute_b32 v21, v42, v19
	ds_bpermute_b32 v17, v42, v15
	ds_bpermute_b32 v12, v42, v10
	ds_bpermute_b32 v8, v42, v6
	ds_bpermute_b32 v13, v42, v11
	ds_bpermute_b32 v9, v42, v7
	s_and_saveexec_b64 s[0:1], s[36:37]
	s_cbranch_execz .LBB0_211
	v_mov_b32_e32 v0, v114
	v_mov_b32_e32 v1, v115
	v_mov_b32_e32 v2, v116
	v_mov_b32_e32 v3, v117
	v_mov_b32_e32 v28, v118
	v_mov_b32_e32 v29, v119
	v_mov_b32_e32 v30, v120
	v_mov_b32_e32 v31, v121
	s_mov_b32 s2, 0x6dc9c883
	s_mov_b32 s3, 0x3fc45f30

; __device__ __forceinline__ void rope_cs(float pos, float inv, float& c, float& s) {
;     ...
;   double rev = (double)ang * 0.15915494309189535; rev -= rint(rev);
; __device__ __forceinline__ void phase_post1(const Params& p, int layer, const int wave_s) {
;     ...
;         float c, s; rope_cs(posv, p.inv_b[(a & 3) * 8 + i], c, s);
	v_mul_f32_e32 v0, v43, v0

; __device__ __forceinline__ u32x4 pack8(const float* x) { u32x4 w; w.x = pk2(x[0], x[1]); w.y = pk2(x[2], x[3]); w.z = pk2(x[4], x[5]); w.w = pk2(x[6], x[7]); return w; }
; __device__ __forceinline__ void rope_cs(float pos, float inv, float& c, float& s) {
;   const float ang = pos * inv;
;   double rev = (double)ang * 0.15915494309189535; rev -= rint(rev);
;   const float fr = (float)rev;
;   s = __builtin_amdgcn_sinf(fr); c = __builtin_amdgcn_cosf(fr);
; }
; __device__ __forceinline__ void phase_post1(const Params& p, int layer, const int wave_s) {
;     ...
;       const float posv = (a < 8) ? rowp : colp;
; #pragma unroll
;       for (int i = 0; i < 8; ++i) { const float y = x[i] * rs * wn[i]; const float other = __shfl_xor(y, 4);
;         float c, s; rope_cs(posv, p.inv_b[(a & 3) * 8 + i], c, s);
;         x[i] = (a & 4) ? other * s + y * c : y * c - other * s; }
;       if (act) *ptr = pack8(x);
	v_mul_f32_e32 v22, v43, v28
	v_cvt_f64_f32_e32 v[22:23], v22
	v_mul_f64 v[24:25], v[22:23], s[2:3]
	v_rndne_f64_e32 v[24:25], v[24:25]
	v_fma_f64 v[22:23], v[22:23], s[2:3], -v[24:25]
	v_cvt_f32_f64_e32 v23, v[22:23]
	v_cos_f32_e32 v22, v23
	v_sin_f32_e32 v24, v23
	v_mul_f32_e32 v23, v43, v29
	v_cvt_f64_f32_e32 v[26:27], v23
	v_mul_f64 v[28:29], v[26:27], s[2:3]
	v_rndne_f64_e32 v[28:29], v[28:29]
	v_fma_f64 v[26:27], v[26:27], s[2:3], -v[28:29]
	v_cvt_f32_f64_e32 v23, v[26:27]
	v_cos_f32_e32 v26, v23
	v_sin_f32_e32 v28, v23
	v_mul_f32_e32 v23, v43, v30
	v_cvt_f64_f32_e32 v[32:33], v23
	v_mul_f64 v[34:35], v[32:33], s[2:3]
	v_rndne_f64_e32 v[34:35], v[34:35]
	v_mul_f32_e32 v27, v43, v31
	v_fma_f64 v[32:33], v[32:33], s[2:3], -v[34:35]
	v_cvt_f64_f32_e32 v[30:31], v27
	v_cvt_f32_f64_e32 v25, v[32:33]
	v_mul_f64 v[32:33], v[30:31], s[2:3]
	v_rndne_f64_e32 v[32:33], v[32:33]
	v_fma_f64 v[30:31], v[30:31], s[2:3], -v[32:33]
	v_cvt_f32_f64_e32 v29, v[30:31]
	v_cvt_f64_f32_e32 v[30:31], v0
	v_mul_f64 v[32:33], v[30:31], s[2:3]
	v_rndne_f64_e32 v[32:33], v[32:33]
	v_fma_f64 v[30:31], v[30:31], s[2:3], -v[32:33]
	v_cvt_f32_f64_e32 v0, v[30:31]
	v_cos_f32_e32 v30, v0
	v_sin_f32_e32 v32, v0
	v_mul_f32_e32 v0, v43, v1
	v_cvt_f64_f32_e32 v[0:1], v0
	v_mul_f64 v[34:35], v[0:1], s[2:3]
	v_rndne_f64_e32 v[34:35], v[34:35]
	v_fma_f64 v[0:1], v[0:1], s[2:3], -v[34:35]
	v_cvt_f32_f64_e32 v1, v[0:1]
	v_cos_f32_e32 v0, v1
	v_sin_f32_e32 v34, v1
	v_mul_f32_e32 v1, v43, v2
	v_cvt_f64_f32_e32 v[36:37], v1
	v_mul_f64 v[44:45], v[36:37], s[2:3]
	v_rndne_f64_e32 v[44:45], v[44:45]
	v_fma_f64 v[36:37], v[36:37], s[2:3], -v[44:45]
	v_cvt_f32_f64_e32 v1, v[36:37]
	v_cos_f32_e32 v31, v1
	v_sin_f32_e32 v33, v1
	v_mul_f32_e32 v1, v43, v3
	v_cvt_f64_f32_e32 v[2:3], v1
	v_mul_f64 v[36:37], v[2:3], s[2:3]
	v_rndne_f64_e32 v[36:37], v[36:37]
	v_fma_f64 v[2:3], v[2:3], s[2:3], -v[36:37]
	v_cvt_f32_f64_e32 v2, v[2:3]
	v_sin_f32_e32 v35, v2
	v_cos_f32_e32 v23, v25
	v_sin_f32_e32 v25, v25
	v_cos_f32_e32 v27, v29
	v_sin_f32_e32 v29, v29
	v_cos_f32_e32 v1, v2
	s_waitcnt lgkmcnt(0)
	v_pk_mul_f32 v[8:9], v[34:35], v[8:9]
	v_pk_mul_f32 v[2:3], v[24:25], v[20:21]
	v_pk_mul_f32 v[12:13], v[32:33], v[12:13]
	v_cndmask_b32_e64 v9, v9, -v9, s[42:43]
	v_cndmask_b32_e64 v8, v8, -v8, s[42:43]
	v_cndmask_b32_e64 v3, v3, -v3, s[42:43]
	v_cndmask_b32_e64 v2, v2, -v2, s[42:43]
	v_pk_mul_f32 v[16:17], v[28:29], v[16:17]
	v_cndmask_b32_e64 v13, v13, -v13, s[42:43]
	v_cndmask_b32_e64 v12, v12, -v12, s[42:43]
	v_pk_fma_f32 v[0:1], v[6:7], v[0:1], v[8:9]
	v_pk_fma_f32 v[2:3], v[18:19], v[22:23], v[2:3]
	v_cndmask_b32_e64 v17, v17, -v17, s[42:43]
	v_cndmask_b32_e64 v16, v16, -v16, s[42:43]
	v_pk_fma_f32 v[10:11], v[10:11], v[30:31], v[12:13]
	v_bfe_u32 v6, v1, 16, 1
	v_bfe_u32 v7, v0, 16, 1
	v_pk_fma_f32 v[14:15], v[14:15], v[26:27], v[16:17]
	v_add3_u32 v0, v0, v7, s15
	v_add3_u32 v1, v1, v6, s15
	v_bfe_u32 v6, v2, 16, 1
	v_bfe_u32 v7, v3, 16, 1
	v_bfe_u32 v12, v10, 16, 1
	v_bfe_u32 v13, v11, 16, 1
	v_bfe_u32 v8, v15, 16, 1
	v_bfe_u32 v9, v14, 16, 1
	v_add3_u32 v11, v11, v13, s15
	v_add3_u32 v10, v10, v12, s15
	v_add3_u32 v3, v3, v7, s15
	v_add3_u32 v2, v2, v6, s15
	v_add3_u32 v9, v14, v9, s15
	v_add3_u32 v8, v15, v8, s15
	v_lshrrev_b32_e32 v6, 16, v2
	v_lshrrev_b32_e32 v7, 16, v3
	v_lshrrev_b32_e32 v2, 16, v10
	v_lshrrev_b32_e32 v3, 16, v11
	v_and_or_b32 v3, v1, s14, v3
	v_and_or_b32 v2, v0, s14, v2
	v_and_or_b32 v1, v8, s14, v7
	v_and_or_b32 v0, v9, s14, v6
	global_store_dwordx4 v[4:5], v[0:3], off
